# phase-4 wave priority: moba waves run at s_setprio 1 (scan and phase-5 waves at 0) so a CU's still-running moba workgroup wins issue arbitration
# speedup vs baseline: 1.0010x; 1.0010x over previous
.Lscan_entry:
	s_setprio 0
	s_mov_b32 s2, 0xfe03f81
	s_mov_b32 s18, 0xcd0000
	s_mov_b64 s[16:17], 0x40800
	s_mov_b32 s19, s76

.LBB0_486:
	s_setprio 1
	v_readlane_b32 s0, v255, 3
	v_readlane_b32 s1, v255, 4
	s_andn2_b64 vcc, exec, s[0:1]
	s_nop 0
	v_cndmask_b32_e64 v0, 0, 1, s[0:1]
	v_cmp_ne_u32_e64 s[38:39], 1, v0
	s_cbranch_vccnz .LBB0_565
	s_not_b32 s2, s76
	s_add_u32 s52, s58, 0x2cd1000
	s_addc_u32 s53, s59, 0
	s_add_u32 s33, s58, 0x8cd1000
	s_addc_u32 s72, s59, 0
	s_add_u32 s73, s58, 0xbd0000
	v_mbcnt_lo_u32_b32 v0, -1, 0
	s_addc_u32 s74, s59, 0
	v_mbcnt_hi_u32_b32 v196, -1, v0
	s_add_u32 s62, s58, 0xcd1000
	v_and_b32_e32 v0, 64, v196
	s_addc_u32 s63, s59, 0
	s_mov_b32 s67, 0
	v_mov_b32_e32 v33, 0
	s_movk_i32 s75, 0xff
	s_movk_i32 s77, 0x1800
	s_mov_b32 s78, 0xefa18f08
	v_xor_b32_e32 v197, 32, v196
	v_add_u32_e32 v198, 64, v0
	v_mov_b32_e32 v199, 0xff800000
	v_mov_b32_e32 v200, 0x3f803f80
	s_mov_b32 s6, 0
	s_mov_b32 s79, 0
	s_branch .LBB0_490

.LBB0_643:
	s_setprio 0
	s_mov_b64 s[98:99], exec
	v_readlane_b32 s100, v255, 1
	v_readlane_b32 s101, v255, 2
	s_nop 1
	s_mov_b64 exec, s[100:101]
	s_cbranch_execz .Lb3w_skip_c
	v_readlane_b32 s100, v255, 11
	s_nop 3
	v_sub_u32_e64 v230, 4, s100
	v_readlane_b32 s100, v255, 5
	v_readlane_b32 s101, v255, 6
	v_mov_b32_e32 v217, 0x3500
	v_mov_b32_e32 v231, 0
	s_nop 4
